# attention loop: per-wave a-priori dead-tile skip (Cauchy-Schwarz bound, bit-identical), lean gating; plus prologue hoist
# baseline (speedup 1.0000x reference)
.LBB0_300:
	s_or_b64 exec, exec, s[4:5]
	s_lshl_b32 s4, s3, 8
	v_readlane_b32 s5, v245, 15
	s_lshl_b32 s69, s3, 2
	s_ashr_i32 s3, s2, 31
	s_add_i32 s68, s4, s5
	s_lshl_b64 s[2:3], s[2:3], 2
	s_sub_u32 s2, s7, s2
	v_mov_b32_e32 v3, s11
	v_mov_b32_e32 v8, s89
	s_subb_u32 s3, s33, s3
	v_mov_b32_e32 v175, 0
	s_waitcnt lgkmcnt(0)
	s_barrier
	ds_read_b128 v[4:7], v3
	ds_read_b128 v[8:11], v8
	v_and_b32_e32 v185, 31, v19
	v_lshrrev_b32_e32 v3, 1, v19
	v_lshlrev_b32_e32 v172, 2, v2
	v_lshlrev_b32_e32 v12, 7, v185
	v_bitop3_b32 v2, v3, v2, 7 bitop3:0x6c
	v_mul_f32_e32 v18, s12, v235
	v_lshl_add_u32 v186, v2, 4, v12
	v_or_b32_e32 v2, s68, v185
	v_cvt_f32_i32_e32 v3, v172
	v_mul_f32_e32 v173, 0x42800000, v18
	s_mov_b32 s56, 0x41600000
	v_cvt_f32_u32_e32 v2, v2
	v_div_scale_f32 v58, s[2:3], v173, v173, s56
	v_cvt_f32_u32_e32 v13, s4
	v_rcp_f32_e32 v60, v58
	s_waitcnt lgkmcnt(1)
	v_max_f32_e32 v5, v5, v5
	v_max_f32_e32 v4, v4, v4
	v_sub_f32_e32 v187, v3, v2
	v_max_f32_e32 v2, v4, v5
	v_max3_f32 v2, v2, v6, v7
	v_fma_f32 v3, -v58, v60, 1.0
	v_add_f32_e32 v176, v187, v13
	s_waitcnt lgkmcnt(0)
	v_max3_f32 v23, v2, v8, v9
	v_fmac_f32_e32 v60, v3, v60
	v_pk_add_f32 v[2:3], v[176:177], s[14:15] op_sel_hi:[0,1]
	v_max3_f32 v23, v23, v10, v11
	v_and_b32_e32 v24, 0x7fffffff, v2
	s_mov_b32 s2, 0xf800000
	v_and_b32_e32 v25, 0x7fffffff, v3
	v_pk_add_f32 v[12:13], v[176:177], s[22:23] op_sel_hi:[0,1]
	v_pk_add_f32 v[14:15], v[176:177], s[24:25] op_sel_hi:[0,1]
	v_pk_add_f32 v[16:17], v[176:177], s[26:27] op_sel_hi:[0,1]
	v_add_f32_e32 v26, 1.0, v176
	v_and_b32_e32 v11, 0x7fffffff, v13
	v_and_b32_e32 v10, 0x7fffffff, v12
	v_and_b32_e32 v13, 0x7fffffff, v15
	v_and_b32_e32 v12, 0x7fffffff, v14
	v_and_b32_e32 v15, 0x7fffffff, v17
	v_and_b32_e32 v14, 0x7fffffff, v16
	v_and_b32_e32 v22, 0x7fffffff, v176
	v_pk_mul_f32 v[16:17], v[14:15], v[18:19] op_sel_hi:[1,0] neg_lo:[0,1] neg_hi:[0,1]
	v_pk_add_f32 v[8:9], v[176:177], s[20:21] op_sel_hi:[0,1]
	v_and_b32_e32 v9, 0x7fffffff, v9
	v_and_b32_e32 v8, 0x7fffffff, v8
	v_readlane_b32 s55, v245, 28
	v_pk_add_f32 v[4:5], v[176:177], s[16:17] op_sel_hi:[0,1]
	v_pk_add_f32 v[6:7], v[176:177], s[18:19] op_sel_hi:[0,1]
	v_xor_b32_e32 v188, 32, v186
	v_and_b32_e32 v5, 0x7fffffff, v5
	v_and_b32_e32 v4, 0x7fffffff, v4
	v_and_b32_e32 v7, 0x7fffffff, v7
	v_and_b32_e32 v6, 0x7fffffff, v6
	v_add_u32_e32 v61, 0, v188
	v_add_u32_e32 v189, s52, v186
	v_add_u32_e32 v192, s52, v188
	v_div_scale_f32 v59, s[4:5], s56, v173, s56
	v_pk_add_f32 v[42:43], v[176:177], s[28:29] op_sel_hi:[0,1]
	v_pk_add_f32 v[44:45], v[176:177], s[30:31] op_sel_hi:[0,1]
	v_pk_add_f32 v[46:47], v[176:177], s[34:35] op_sel_hi:[0,1]
	v_pk_add_f32 v[48:49], v[176:177], s[36:37] op_sel_hi:[0,1]
	v_pk_add_f32 v[50:51], v[176:177], s[38:39] op_sel_hi:[0,1]
	v_pk_add_f32 v[52:53], v[176:177], s[40:41] op_sel_hi:[0,1]
	v_pk_add_f32 v[54:55], v[176:177], s[42:43] op_sel_hi:[0,1]
	v_pk_add_f32 v[56:57], v[176:177], s[44:45] op_sel_hi:[0,1]
	v_and_b32_e32 v57, 0x7fffffff, v57
	v_and_b32_e32 v56, 0x7fffffff, v56
	v_and_b32_e32 v55, 0x7fffffff, v55
	v_and_b32_e32 v54, 0x7fffffff, v54
	v_and_b32_e32 v53, 0x7fffffff, v53
	v_and_b32_e32 v52, 0x7fffffff, v52
	v_and_b32_e32 v51, 0x7fffffff, v51
	v_and_b32_e32 v50, 0x7fffffff, v50
	v_and_b32_e32 v49, 0x7fffffff, v49
	v_and_b32_e32 v48, 0x7fffffff, v48
	v_and_b32_e32 v47, 0x7fffffff, v47
	v_and_b32_e32 v46, 0x7fffffff, v46
	v_and_b32_e32 v45, 0x7fffffff, v45
	s_waitcnt vmcnt(4)
	v_mul_f32_e32 v2, v23, v249
	v_mul_f32_e32 v3, 0x4f800000, v2
	v_cmp_gt_f32_e32 vcc, s2, v2
	v_and_b32_e32 v23, 0x7fffffff, v26
	v_and_b32_e32 v44, 0x7fffffff, v44
	v_cndmask_b32_e32 v21, v2, v3, vcc
	v_sqrt_f32_e32 v27, v21
	v_pk_mul_f32 v[2:3], v[22:23], v[18:19] op_sel_hi:[1,0] neg_lo:[0,1] neg_hi:[0,1]
	v_and_b32_e32 v43, 0x7fffffff, v43
	v_and_b32_e32 v42, 0x7fffffff, v42
	v_add_u32_e32 v14, -1, v27
	v_add_u32_e32 v15, 1, v27
	v_fma_f32 v22, -v14, v27, v21
	v_fma_f32 v23, -v15, v27, v21
	v_cmp_ge_f32_e64 s[2:3], 0, v22
	v_pk_mul_f32 v[96:97], v[42:43], v[18:19] op_sel_hi:[1,0] neg_lo:[0,1] neg_hi:[0,1]
	v_pk_mul_f32 v[94:95], v[44:45], v[18:19] op_sel_hi:[1,0] neg_lo:[0,1] neg_hi:[0,1]
	v_cndmask_b32_e64 v14, v27, v14, s[2:3]
	v_cmp_lt_f32_e64 s[2:3], 0, v23
	v_pk_mul_f32 v[92:93], v[46:47], v[18:19] op_sel_hi:[1,0] neg_lo:[0,1] neg_hi:[0,1]
	v_pk_mul_f32 v[90:91], v[48:49], v[18:19] op_sel_hi:[1,0] neg_lo:[0,1] neg_hi:[0,1]
	v_cndmask_b32_e64 v14, v14, v15, s[2:3]
	v_mul_f32_e32 v15, 0x37800000, v14
	v_cndmask_b32_e32 v14, v14, v15, vcc
	v_cmp_class_f32_e32 vcc, v21, v232
	v_pk_mul_f32 v[88:89], v[50:51], v[18:19] op_sel_hi:[1,0] neg_lo:[0,1] neg_hi:[0,1]
	v_pk_mul_f32 v[86:87], v[52:53], v[18:19] op_sel_hi:[1,0] neg_lo:[0,1] neg_hi:[0,1]
	v_cndmask_b32_e32 v14, v14, v21, vcc
	v_mul_f32_e32 v21, 0x3f828f5c, v14
	v_fma_f32 v246, v18, 4.0, v21
	s_mov_b32 s99, 0
	v_readfirstlane_b32 s98, v246
	s_mov_b32 s100, 0
	s_mov_b32 s101, 0
	v_fmaak_f32 v22, 2.0, v21, 0x42000000
	v_div_scale_f32 v23, s[2:3], v18, v18, v22
	v_rcp_f32_e32 v26, v23
	v_pk_mul_f32 v[14:15], v[12:13], v[18:19] op_sel_hi:[1,0] neg_lo:[0,1] neg_hi:[0,1]
	v_div_scale_f32 v12, vcc, v22, v18, v22
	v_fma_f32 v13, -v23, v26, 1.0
	v_fmac_f32_e32 v26, v13, v26
	v_mul_f32_e32 v13, v12, v26
	v_fma_f32 v27, -v23, v13, v12
	v_fmac_f32_e32 v13, v27, v26
	v_fma_f32 v12, -v23, v13, v12
	v_div_fmas_f32 v12, v12, v26, v13
	v_div_fixup_f32 v22, v12, v18, v22
	v_cvt_i32_f32_e32 v23, v22
	v_cmp_gt_f32_e32 vcc, s90, v22
	v_pk_mul_f32 v[12:13], v[10:11], v[18:19] op_sel_hi:[1,0] neg_lo:[0,1] neg_hi:[0,1]
	v_pk_mul_f32 v[10:11], v[8:9], v[18:19] op_sel_hi:[1,0] neg_lo:[0,1] neg_hi:[0,1]
	v_readfirstlane_b32 s2, v23
	s_add_i32 s12, s2, 1
	s_and_b64 s[2:3], vcc, exec
	s_cselect_b32 s2, s12, 0x2000
	s_add_i32 s12, s2, 62
	s_add_i32 s2, s2, -2
	s_ashr_i32 s12, s12, 6
	s_ashr_i32 s2, s2, 6
	s_xor_b32 s3, s69, 60
	s_min_i32 s77, s69, s12
	s_add_i32 s2, s2, 1
	s_min_i32 s2, s3, s2
	s_add_i32 s82, s77, 4
	s_add_u32 s12, s80, 0x30000
	s_addc_u32 s13, s81, 0
	s_add_u32 s12, s80, 0x60000
	v_readlane_b32 s13, v245, 27
	s_addc_u32 s13, s81, 0
	v_add_u32_e32 v26, 0, v186
	v_readlane_b32 s12, v245, 29
	v_readlane_b32 s12, v245, 30
	v_pk_mul_f32 v[8:9], v[6:7], v[18:19] op_sel_hi:[1,0] neg_lo:[0,1] neg_hi:[0,1]
	v_pk_mul_f32 v[6:7], v[4:5], v[18:19] op_sel_hi:[1,0] neg_lo:[0,1] neg_hi:[0,1]
	v_pk_mul_f32 v[4:5], v[24:25], v[18:19] op_sel_hi:[1,0] neg_lo:[0,1] neg_hi:[0,1]
	ds_read_b128 v[22:25], v26
	ds_read_b128 v[26:29], v26 offset:4096
	ds_read_b128 v[30:33], v61
	ds_read_b128 v[34:37], v189
	ds_read_b128 v[38:41], v192
	s_waitcnt lgkmcnt(1)
	v_mfma_f32_32x32x16_bf16 v[98:113], v[22:25], v[34:37], v[2:17]
	v_mul_f32_e32 v22, v59, v60
	v_fma_f32 v23, -v58, v22, v59
	v_fmac_f32_e32 v22, v23, v60
	v_mul_f32_e64 v84, v54, -v18
	v_mul_f32_e64 v85, v55, -v18
	v_pk_mul_f32 v[82:83], v[56:57], v[18:19] op_sel_hi:[1,0] neg_lo:[0,1] neg_hi:[0,1]
	v_fma_f32 v23, -v58, v22, v59
	s_mov_b64 vcc, s[4:5]
	v_mfma_f32_32x32x16_bf16 v[82:97], v[26:29], v[34:37], v[82:97]
	v_div_fmas_f32 v26, v23, v60, v22
	ds_read_b128 v[22:25], v61 offset:4096
	v_div_fixup_f32 v26, v26, v173, s56
	v_cmp_gt_f32_e32 vcc, s24, v21
	s_add_i32 s83, s82, s2
	s_cmp_lt_i32 s83, 1
	v_cndmask_b32_e32 v21, 0, v26, vcc
	s_waitcnt lgkmcnt(1)
	v_mfma_f32_32x32x16_bf16 v[98:113], v[30:33], v[38:41], v[98:113]
	v_min_f32_e32 v21, 0x42800000, v21
	s_nop 0
	v_readfirstlane_b32 s3, v21
	s_waitcnt lgkmcnt(0)
	v_mfma_f32_32x32x16_bf16 v[82:97], v[22:25], v[38:41], v[82:97]
	s_cbranch_scc1 .LBB0_350
	v_lshrrev_b32_e32 v21, 2, v19
	v_lshlrev_b32_e32 v19, 1, v19
	v_cvt_i32_f32_e32 v193, s3
	v_and_or_b32 v21, v21, 3, v172
	v_and_or_b32 v19, v19, 32, v20
	v_lshl_or_b32 v19, v21, 6, v19
	v_mov_b32_e32 v50, v1
	v_mov_b32_e32 v51, v1
	v_mov_b32_e32 v64, v1
	v_mov_b32_e32 v65, v1
	v_xor_b32_e32 v178, 0x80000000, v18
	v_add_u32_e32 v195, 0x2000, v19
	v_mul_f32_e32 v196, 0x42000000, v18
	v_mul_f32_e32 v197, 0xc2000000, v18
	s_add_i32 s86, s2, s77
	v_mov_b32_e32 v52, v1
	v_mov_b32_e32 v53, v1
	v_mov_b32_e32 v54, v1
	v_mov_b32_e32 v55, v1
	v_mov_b32_e32 v56, v1
	v_mov_b32_e32 v57, v1
	v_mov_b32_e32 v58, v1
	v_mov_b32_e32 v59, v1
	v_mov_b32_e32 v60, v1
	v_mov_b32_e32 v61, v1
	v_mov_b32_e32 v62, v1
	v_mov_b32_e32 v63, v1
	v_mov_b64_e32 v[18:19], v[50:51]
	v_mov_b64_e32 v[80:81], v[64:65]
	v_mov_b64_e32 v[34:35], v[50:51]
	v_mov_b32_e32 v180, v178
	v_mov_b32_e32 v181, v178
	v_xor_b32_e32 v194, 64, v186
	s_sub_i32 s84, s69, s77
	s_or_b32 s85, s69, 3
	v_xor_b32_e32 v198, 0x60, v186
	s_add_i32 s86, s86, 4
	s_add_i32 s87, s77, 3
	s_mov_b32 s88, 0
	v_mov_b32_e32 v174, v1
	v_mov_b32_e32 v175, v1
	v_mov_b32_e32 v182, 0
	s_mov_b32 s89, s69
	v_mov_b64_e32 v[20:21], v[52:53]
	v_mov_b64_e32 v[22:23], v[54:55]
	v_mov_b64_e32 v[24:25], v[56:57]
	v_mov_b64_e32 v[26:27], v[58:59]
	v_mov_b64_e32 v[28:29], v[60:61]
	v_mov_b64_e32 v[30:31], v[62:63]
	v_mov_b64_e32 v[32:33], v[64:65]
	v_mov_b64_e32 v[78:79], v[62:63]
	v_mov_b64_e32 v[76:77], v[60:61]
	v_mov_b64_e32 v[74:75], v[58:59]
	v_mov_b64_e32 v[72:73], v[56:57]
	v_mov_b64_e32 v[70:71], v[54:55]
	v_mov_b64_e32 v[68:69], v[52:53]
	v_mov_b64_e32 v[66:67], v[50:51]
	v_mov_b64_e32 v[36:37], v[52:53]
	v_mov_b64_e32 v[38:39], v[54:55]
	v_mov_b64_e32 v[40:41], v[56:57]
	v_mov_b64_e32 v[42:43], v[58:59]
	v_mov_b64_e32 v[44:45], v[60:61]
	v_mov_b64_e32 v[46:47], v[62:63]
	v_mov_b64_e32 v[48:49], v[64:65]
	s_mov_b32 s90, 0
	s_add_i32 s2, s90, 2
	s_cmp_ge_i32 s2, s83
	s_mov_b64 s[2:3], -1
	s_cbranch_scc0 .LBB0_303

.LBB0_310:
	s_cmp_lg_u32 s100, 0
	s_cbranch_scc1 .Lc1_skipA
	s_cmp_lt_i32 s90, s82
	s_cselect_b64 s[4:5], -1, 0
	s_add_i32 s12, s88, 0
	v_add_u32_e32 v114, s12, v194
	ds_read_b128 v[158:161], v114
	ds_read_b128 v[150:153], v114 offset:4096
	v_add_u32_e32 v114, s12, v198
	ds_read_b128 v[154:157], v114
	ds_read_b128 v[146:149], v114 offset:4096
	v_add_u32_e32 v114, s52, v194
	v_add_u32_e32 v115, s52, v198
	ds_read_b128 v[166:169], v114
	ds_read_b128 v[162:165], v115
	s_cmp_lt_u32 s90, 4
	s_cselect_b64 s[2:3], -1, 0
	s_mov_b64 s[12:13], -1
	s_and_b64 vcc, exec, s[2:3]
	s_cbranch_vccnz .LBB0_312
	v_cndmask_b32_e64 v114, v197, v196, s[4:5]
	v_pk_add_f32 v[128:129], v[114:115], v[16:17] op_sel_hi:[0,1]
	v_pk_add_f32 v[126:127], v[114:115], v[14:15] op_sel_hi:[0,1]
	v_pk_add_f32 v[124:125], v[114:115], v[12:13] op_sel_hi:[0,1]
	v_pk_add_f32 v[122:123], v[114:115], v[10:11] op_sel_hi:[0,1]
	v_pk_add_f32 v[120:121], v[114:115], v[8:9] op_sel_hi:[0,1]
	v_pk_add_f32 v[118:119], v[114:115], v[6:7] op_sel_hi:[0,1]
	v_pk_add_f32 v[116:117], v[114:115], v[4:5] op_sel_hi:[0,1]
	v_pk_add_f32 v[114:115], v[114:115], v[2:3] op_sel_hi:[0,1]
	s_mov_b64 s[12:13], 0

.LBB0_334:
	s_cmp_lg_u32 s99, 0
	s_cbranch_scc1 .Lc1_p1

.LBB0_339:
	s_cmp_lg_u32 s100, 0
	s_cbranch_scc1 .LBB0_341
	s_and_b64 vcc, exec, s[4:5]
	s_mov_b64 s[2:3], -1
	s_cbranch_vccz .LBB0_342
	s_and_b64 vcc, exec, s[2:3]
	s_cbranch_vccnz .LBB0_345

.LBB0_346:
	s_mov_b32 s100, s101
	s_mov_b32 s101, 0
	s_mov_b32 s90, s12
	s_add_i32 s2, s90, 2
	s_cmp_ge_i32 s2, s83
	s_mov_b64 s[2:3], -1
	s_cbranch_scc1 .LBB0_302
	s_branch .LBB0_303
.Lc1_dead1:
	s_mov_b32 s99, 1
	s_branch .LBB0_341
.Lc1_skipA:
	s_mov_b64 s[2:3], 0
	s_branch .LBB0_321
.Lc1_p1:
	s_cmp_eq_u32 s12, s82
	s_cbranch_scc1 .Lc1_p1reset
	s_cmp_lt_u32 s12, 4
	s_cbranch_scc1 .Lc1_qkB
	s_cmp_lt_i32 s12, s82
	s_cbranch_scc1 .Lc1_left
	v_add_f32_e32 v246, s98, v2
	s_branch .Lc1_tst
.Lc1_left:
	v_add_f32_e32 v246, v17, v196
	v_add_f32_e32 v246, s98, v246
.Lc1_tst:
	v_exp_f32_e32 v246, v246
	v_min_f32_e32 v247, v174, v175
	s_nop 0
	v_mul_f32_e32 v246, 0x4f800000, v246
	v_cmp_ge_f32_e32 vcc, v246, v247
	s_cmp_lg_u64 vcc, 0
	s_cbranch_scc1 .Lc1_qkB
	s_mov_b32 s101, 1
	s_branch .LBB0_339
.Lc1_p1reset:
	s_mov_b32 s99, 0
	s_branch .Lc1_qkB
